# mixer: workgroups 256-287 (CU partners of the 32 scan workgroups) stay idle and the other 448 take all attention/sample/copy items; scan W/U/g operand loads issued mid-step (1.5-step lead)
# speedup vs baseline: 1.1210x; 1.0151x over previous
; __device__ __forceinline__ int tid_() { int t = threadIdx.x; asm volatile("" : "+v"(t)); return t; }
; __device__ void ph_mixer(const P& p, u16* lds) {
;   const int NSCAN = 32;
;     ...
;   if ((int)blockIdx.x < NSCAN) { if (MIXMASK & 1) scan_seq(p, blockIdx.x, lds); return; }
;   const int NA = 2048, NSA = 256, NSD = 256, NCP = 2409;
;   const int st = gridDim.x - NSCAN, b0 = blockIdx.x - NSCAN;
;   auto first = [&](int off) { int f = b0 - (off % st); return f < 0 ? f + st : f; };
;   if (MIXMASK & 8) for (int it = first(0); it < NSD; it += st) dn_sample_wave(p, it * 4 + (tid_() >> 6));
;   if (MIXMASK & 4) for (int it = first(224); it < NSA; it += st) attn_sample_item(p, it, lds);
;   if (MIXMASK & 2) for (int it = first(288); it < NA; it += st) attn_prompt_item(p, it, lds);
;   if (MIXMASK & 16) for (int it = first(256); it < NCP; it += st) copy_item(p, it);
.LBB0_300:
	s_cmp_lt_i32 s6, 4
	s_cselect_b64 s[0:1], -1, 0
	s_cmp_gt_i32 s7, 3
	s_cselect_b64 s[2:3], -1, 0
	s_and_b64 s[0:1], s[0:1], s[2:3]
	s_andn2_b64 vcc, exec, s[0:1]
	s_cbranch_vccnz .LBB0_539
	v_readlane_b32 s2, v228, 0
	v_readlane_b32 s0, v228, 10
	s_nop 1
	v_writelane_b32 v227, s2, 60
	v_writelane_b32 v227, s0, 61
	s_cmp_gt_i32 s2, 31
	s_mov_b64 s[0:1], -1
	v_readlane_b32 s3, v228, 1
	s_cbranch_scc0 .LBB0_478
	s_cmpk_lt_u32 s2, 0x100
	s_cbranch_scc1 .Lmx_keep
	s_cmpk_lt_u32 s2, 0x120
	s_cbranch_scc1 .LBB0_485
	s_sub_i32 s2, s2, 32
.Lmx_keep:
	v_readlane_b32 s0, v228, 10
	s_nop 1
	s_sub_i32 s0, s0, 32
	s_nop 1
	v_writelane_b32 v228, s2, 0
	v_writelane_b32 v228, s0, 10
	s_nop 1
	v_readlane_b32 s0, v228, 10
	s_sub_i32 s0, s0, 32
	v_readlane_b32 s1, v228, 11
	v_writelane_b32 v227, s0, 1
	s_sub_i32 s0, s2, 32
	s_cmpk_gt_u32 s2, 0x11f
	v_writelane_b32 v227, s0, 11
	s_cbranch_scc1 .LBB0_309
	v_readlane_b32 s0, v228, 2
	v_readlane_b32 s4, v228, 6
	v_readlane_b32 s1, v228, 3
	v_readlane_b32 s5, v228, 7
	s_add_u32 s0, s4, 0x9752000
	v_readlane_b32 s6, v228, 8
	s_addc_u32 s1, s5, 0
	v_readlane_b32 s7, v228, 9
	s_add_u32 s4, s6, 0x8140600
	v_writelane_b32 v227, s0, 3
	s_addc_u32 s5, s7, 0
	v_readlane_b32 s2, v228, 4
	v_writelane_b32 v227, s1, 4
	s_add_u32 s0, s6, 0x8140000
	s_addc_u32 s1, s7, 0
	v_readlane_b32 s3, v228, 5
	s_add_u32 s2, s6, 0x177c8400
	s_addc_u32 s3, s7, 0
	v_writelane_b32 v227, s2, 7
	v_mov_b32_e32 v1, 0
	s_movk_i32 s18, 0x1000
	v_writelane_b32 v227, s3, 8
	v_readlane_b32 s2, v228, 0
	v_readlane_b32 s3, v228, 1
	s_lshl_b32 s14, s2, 2
	v_readlane_b32 s2, v228, 10
	s_lshl_b32 s2, s2, 2
	s_add_i32 s15, s14, 0xffffff80
	v_writelane_b32 v227, s2, 9
	s_addk_i32 s2, 0xff80
	v_writelane_b32 v227, s2, 12
	v_writelane_b32 v227, s4, 5
	s_movk_i32 s22, 0x1620
	v_mov_b64_e32 v[4:5], s[0:1]
	v_writelane_b32 v227, s5, 6
	v_mov_b64_e32 v[2:3], s[4:5]
	s_movk_i32 s1, 0x3000
	v_mov_b32_e32 v9, 0x3ecc95a3
	v_mov_b32_e32 v170, 0x358637bd
	s_mov_b32 s23, 0x800000
	v_mov_b32_e32 v6, 0x3f317218
	v_mov_b32_e32 v171, 0x7f800000
	v_mov_b32_e32 v172, 0x7fc00000
	v_mov_b32_e32 v173, 0xff800000
	v_readlane_b32 s24, v227, 11
	v_readlane_b32 s3, v228, 11
	s_branch .LBB0_305

; __device__ __forceinline__ int tid_() { int t = threadIdx.x; asm volatile("" : "+v"(t)); return t; }
; __device__ __forceinline__ void scan_load(const ScanCtx& c, int n, bf16x8 (&W_)[2], bf16x8 (&QH_)[2], bf16x8 (&QK_)[2],
;                                           bf16x8 (&KT_)[2], f32x4 (&U_)[4], float& g_) {
;   n = n < 128 ? n : 127;
;   const size_t cb = (size_t)(c.seq * 128 + n) * 4096;
; #pragma unroll
;   for (int kb = 0; kb < 2; ++kb) {
;     const size_t o = cb + ((c.w * 2 + kb) * 64 + c.lane) * 8;
;     W_[kb] = *(const bf16x8*)(c.DNW + o); QH_[kb] = *(const bf16x8*)(c.DNQH + o); QK_[kb] = *(const bf16x8*)(c.DNQK + o); KT_[kb] = *(const bf16x8*)(c.DNKT + o);
;   }
; #pragma unroll
;   for (int nt = 0; nt < 4; ++nt) U_[nt] = *(const f32x4*)(c.Ubuf + cb + ((c.w * 4 + nt) * 64 + c.lane) * 4);
;   g_ = c.glp[c.seq * 128 + n];
; }
; __device__ void scan_seq(const P& p, int seq, u16* lds) {
;   const int tid = tid_(), lane = tid & 63, w = tid >> 6, fr = lane & 15, fq = lane >> 4;
;   u16* Sb0 = lds; u16* Sb1 = lds + 4096;
;   ScanCtx c;
;   c.DNW = (const u16*)p.out;
;   c.DNQH = c.DNW + (size_t)4096 * 4096;
;   c.DNQK = c.DNQH + (size_t)4096 * 4096;
;   c.DNKT = c.DNQK + (size_t)4096 * 4096;
;   c.Ubuf = (const float*)p_Abf; c.Obuf = p_Obuf; c.glp = p_gl; c.Vbuf = lds + 8192;
;   c.seq = seq; c.w = w; c.lane = lane;
;   __syncthreads();
;   for (int i = tid; i < 4096 / 2; i += 256) ((unsigned*)Sb0)[i] = 0u;
;   f32x4 S[4];
; #pragma unroll
;   for (int nt = 0; nt < 4; ++nt) S[nt] = f32x4{0.f, 0.f, 0.f, 0.f};
;   bf16x8 Wa[2], QHa[2], QKa[2], KTa[2]; f32x4 Ua[4]; float ga;
;   bf16x8 Wb[2], QHb[2], QKb[2], KTb[2]; f32x4 Ub[4]; float gb;
;   unsigned tr[7] = {0u, 0u, 0u, 0u, 0u, 0u, 0u};
;   scan_load(c, 0, Wa, QHa, QKa, KTa, Ua, ga);
;   scan_load(c, 1, Wb, QHb, QKb, KTb, Ub, gb);
;   __syncthreads();
.LBB0_482:
	s_or_b64 exec, exec, s[0:1]
	v_readlane_b32 s16, v228, 2
	v_readlane_b32 s20, v228, 6
	v_readlane_b32 s21, v228, 7
	s_add_u32 s0, s20, 0x2000000
	s_addc_u32 s1, s21, 0
	s_add_u32 s2, s20, 0x4000000
	s_addc_u32 s3, s21, 0
	s_add_u32 s4, s20, 0x6000000
	v_readlane_b32 s22, v228, 8
	s_addc_u32 s5, s21, 0
	v_readlane_b32 s23, v228, 9
	s_add_u32 s6, s22, 0x3f40000
	s_addc_u32 s7, s23, 0
	v_and_b32_e32 v100, 63, v123
	v_ashrrev_i32_e32 v124, 6, v123
	s_add_u32 s10, s22, 0x179c8000
	v_readlane_b32 s8, v228, 0
	s_addc_u32 s11, s23, 0
	v_readlane_b32 s9, v228, 1
	s_lshl_b32 s8, s8, 7
	v_lshlrev_b32_e32 v101, 10, v124
	v_lshlrev_b32_e32 v102, 3, v100
	s_ashr_i32 s9, s8, 31
	v_or_b32_e32 v112, v101, v102
	s_lshl_b64 s[12:13], s[8:9], 12
	v_ashrrev_i32_e32 v113, 31, v112
	v_lshl_add_u64 v[0:1], s[12:13], 0, v[112:113]
	v_lshlrev_b64 v[8:9], 1, v[0:1]
	v_or_b32_e32 v114, 0x200, v112
	v_lshl_add_u64 v[12:13], s[0:1], 0, v[8:9]
	v_ashrrev_i32_e32 v115, 31, v114
	v_lshl_add_u64 v[10:11], s[20:21], 0, v[8:9]
	v_lshl_add_u64 v[14:15], s[2:3], 0, v[8:9]
	global_load_dwordx4 v[4:7], v[12:13], off
	global_load_dwordx4 v[0:3], v[14:15], off
	v_lshl_add_u64 v[12:13], s[4:5], 0, v[8:9]
	v_lshl_add_u64 v[8:9], s[12:13], 0, v[114:115]
	v_lshlrev_b64 v[14:15], 1, v[8:9]
	v_lshl_add_u64 v[20:21], s[0:1], 0, v[14:15]
	v_lshl_add_u64 v[24:25], s[2:3], 0, v[14:15]
	global_load_dwordx4 v[52:55], v[10:11], off
	global_load_dwordx4 v[48:51], v[10:11], off offset:1024
	s_nop 0
	global_load_dwordx4 v[8:11], v[12:13], off
	global_load_dwordx4 v[16:19], v[20:21], off
	v_lshl_add_u64 v[26:27], s[4:5], 0, v[14:15]
	global_load_dwordx4 v[20:23], v[24:25], off
	global_load_dwordx4 v[12:15], v[26:27], off
	s_lshl_b64 s[12:13], s[8:9], 14
	v_lshl_or_b32 v24, v100, 2, v101
	s_add_u32 s14, s6, s12
	v_ashrrev_i32_e32 v25, 31, v24
	s_addc_u32 s15, s7, s13
	v_lshlrev_b64 v[96:97], 2, v[24:25]
	v_lshl_add_u64 v[24:25], s[14:15], 0, v[96:97]
	s_lshl_b64 s[14:15], s[8:9], 2
	s_add_u32 s14, s10, s14
	s_addc_u32 s15, s11, s15
	v_mov_b32_e32 v125, 0
	global_load_dwordx4 v[76:79], v[24:25], off
	global_load_dwordx4 v[72:75], v[24:25], off offset:1024
	global_load_dwordx4 v[68:71], v[24:25], off offset:2048
	global_load_dwordx4 v[64:67], v[24:25], off offset:3072
	global_load_dwordx2 v[118:119], v125, s[14:15]
	s_or_b32 s14, s8, 1
	v_readlane_b32 s17, v228, 3
	s_ashr_i32 s15, s14, 31
	s_lshl_b64 s[16:17], s[14:15], 12
	v_lshl_add_u64 v[24:25], s[16:17], 0, v[112:113]
	v_lshlrev_b64 v[32:33], 1, v[24:25]
	v_lshl_add_u64 v[36:37], s[0:1], 0, v[32:33]
	s_lshl_b64 s[14:15], s[14:15], 14
	v_lshl_add_u64 v[34:35], s[20:21], 0, v[32:33]
	v_lshl_add_u64 v[38:39], s[2:3], 0, v[32:33]
	global_load_dwordx4 v[28:31], v[36:37], off
	global_load_dwordx4 v[24:27], v[38:39], off
	v_lshl_add_u64 v[36:37], s[4:5], 0, v[32:33]
	v_lshl_add_u64 v[32:33], s[16:17], 0, v[114:115]
	s_add_u32 s14, s6, s14
	v_lshlrev_b64 v[38:39], 1, v[32:33]
	s_addc_u32 s15, s7, s15
	v_lshl_add_u64 v[44:45], s[0:1], 0, v[38:39]
	v_lshl_add_u64 v[80:81], s[2:3], 0, v[38:39]
	v_lshl_add_u64 v[82:83], s[4:5], 0, v[38:39]
	v_lshl_add_u64 v[98:99], s[14:15], 0, v[96:97]
	global_load_dwordx4 v[60:63], v[34:35], off
	global_load_dwordx4 v[56:59], v[34:35], off offset:1024
	s_nop 0
	global_load_dwordx4 v[32:35], v[36:37], off
	global_load_dwordx4 v[40:43], v[44:45], off
	s_nop 0
	global_load_dwordx4 v[44:47], v[80:81], off
	global_load_dwordx4 v[36:39], v[82:83], off
	global_load_dwordx4 v[92:95], v[98:99], off
	global_load_dwordx4 v[88:91], v[98:99], off offset:1024
	global_load_dwordx4 v[84:87], v[98:99], off offset:2048
	s_nop 0
	global_load_dwordx4 v[80:83], v[98:99], off offset:3072
	s_or_b32 s8, s8, 2
	s_mov_b32 s9, 0x7ffff800
	v_lshlrev_b32_e32 v99, 3, v124
	v_lshl_add_u64 v[116:117], s[6:7], 0, v[96:97]
	s_add_u32 s6, s22, s12
	v_and_or_b32 v98, v101, s9, v102
	v_and_b32_e32 v99, 8, v99
	s_addc_u32 s7, s23, s13
	v_lshl_or_b32 v127, v98, 1, v99
	v_lshl_or_b32 v98, v112, 1, v99
	v_lshl_add_u64 v[96:97], s[6:7], 0, v[96:97]
	s_mov_b64 s[6:7], 0x179f5200
	v_lshlrev_b32_e32 v126, 4, v100
	v_or_b32_e32 v128, 0x800, v98
	v_or_b32_e32 v129, 0xc00, v98
	v_lshl_add_u64 v[120:121], v[96:97], 0, s[6:7]
	s_mov_b32 s12, -2
	s_movk_i32 s9, 0xc000
	s_mov_b64 s[6:7], 0x8000
	v_mov_b32_e32 v96, 0
	v_mov_b32_e32 v97, v125
	v_mov_b32_e32 v98, v125
	v_mov_b32_e32 v99, v125
	v_mov_b32_e32 v100, 0
	v_mov_b32_e32 v101, v125
	v_mov_b32_e32 v102, v125
	v_mov_b32_e32 v103, v125
	v_mov_b32_e32 v104, 0
	v_mov_b32_e32 v105, v125
	v_mov_b32_e32 v106, v125
	v_mov_b32_e32 v107, v125
	v_mov_b32_e32 v108, 0
	v_mov_b32_e32 v109, v125
	v_mov_b32_e32 v110, v125
	v_mov_b32_e32 v111, v125
	v_readlane_b32 s18, v228, 4
	v_readlane_b32 s19, v228, 5
	s_waitcnt lgkmcnt(0)
	s_barrier
	s_waitcnt vmcnt(0)
	v_mov_b32_e32 v170, v52
	v_mov_b32_e32 v171, v53
	v_mov_b32_e32 v172, v54
	v_mov_b32_e32 v173, v55
	v_mov_b32_e32 v174, v48
	v_mov_b32_e32 v175, v49
	v_mov_b32_e32 v176, v50
	v_mov_b32_e32 v177, v51
	v_mov_b32_e32 v178, v76
	v_mov_b32_e32 v179, v77
	v_mov_b32_e32 v180, v78
	v_mov_b32_e32 v181, v79
	v_mov_b32_e32 v182, v72
	v_mov_b32_e32 v183, v73
	v_mov_b32_e32 v184, v74
	v_mov_b32_e32 v185, v75
	v_mov_b32_e32 v186, v68
	v_mov_b32_e32 v187, v69
	v_mov_b32_e32 v188, v70
	v_mov_b32_e32 v189, v71
	v_mov_b32_e32 v190, v64
	v_mov_b32_e32 v191, v65
	v_mov_b32_e32 v192, v66
	v_mov_b32_e32 v193, v67
	v_mov_b32_e32 v194, v118
	v_mov_b32_e32 v196, v60
	v_mov_b32_e32 v197, v61
	v_mov_b32_e32 v198, v62
	v_mov_b32_e32 v199, v63
	v_mov_b32_e32 v200, v56
	v_mov_b32_e32 v201, v57
	v_mov_b32_e32 v202, v58
	v_mov_b32_e32 v203, v59
	v_mov_b32_e32 v204, v92
	v_mov_b32_e32 v205, v93
	v_mov_b32_e32 v206, v94
	v_mov_b32_e32 v207, v95
	v_mov_b32_e32 v208, v88
	v_mov_b32_e32 v209, v89
	v_mov_b32_e32 v210, v90
	v_mov_b32_e32 v211, v91
	v_mov_b32_e32 v212, v84
	v_mov_b32_e32 v213, v85
	v_mov_b32_e32 v214, v86
	v_mov_b32_e32 v215, v87
	v_mov_b32_e32 v216, v80
	v_mov_b32_e32 v217, v81
	v_mov_b32_e32 v218, v82
	v_mov_b32_e32 v219, v83
	v_mov_b32_e32 v195, v119
	v_mov_b32_e32 v122, v119
; __device__ __forceinline__ uint2 pack4v(f32x4 a) { uint2 r; r.x = pack2(a[0], a[1]); r.y = pack2(a[2], a[3]); return r; }
; __device__ __forceinline__ f32x4 mfma16(bf16x8 a, bf16x8 b, f32x4 c) { return __builtin_amdgcn_mfma_f32_16x16x32_bf16(a, b, c, 0, 0, 0); }
; __device__ __forceinline__ void scan_step(const ScanCtx& c, int n, const u16* Sc, u16* Sn, f32x4 (&S)[4], bf16x8 (&W_)[2], ...
;   const int w = c.w, lane = c.lane;
;   const size_t cb = (size_t)(c.seq * 128 + n) * 4096;
;   bf16x8 Sf[2][4];
; #pragma unroll
;   for (int kb = 0; kb < 2; ++kb)
; #pragma unroll
;     for (int nt = 0; nt < 4; ++nt) Sf[kb][nt] = *(const bf16x8*)(Sc + ((kb * 4 + nt) * 64 + lane) * 8);
; #pragma unroll
;   for (int nt = 0; nt < 4; ++nt) {
;     f32x4 a = {0.f, 0.f, 0.f, 0.f};
;     a = mfma16(W_[0], Sf[0][nt], a); a = mfma16(W_[1], Sf[1][nt], a);
;     f32x4 vn = U_[nt] - a;
;     *(uint2*)(c.Vbuf + (((w >> 1) * 4 + nt) * 64 + lane) * 8 + (w & 1) * 4) = pack4v(vn);
;   }
;   __syncthreads();
;   bf16x8 Vf[2][4];
; #pragma unroll
;   for (int kb = 0; kb < 2; ++kb)
; #pragma unroll
;     for (int nt = 0; nt < 4; ++nt) Vf[kb][nt] = *(const bf16x8*)(c.Vbuf + ((kb * 4 + nt) * 64 + lane) * 8);
;   const float glc = g_;
.LBB0_483:
	ds_read_b128 v[130:133], v126
	ds_read_b128 v[134:137], v126 offset:1024
	ds_read_b128 v[142:145], v126 offset:2048
	ds_read_b128 v[146:149], v126 offset:3072
	ds_read_b128 v[150:153], v126 offset:4096
	ds_read_b128 v[158:161], v126 offset:5120
	ds_read_b128 v[162:165], v126 offset:6144
	ds_read_b128 v[166:169], v126 offset:7168
	s_waitcnt vmcnt(19)
	v_mov_b32_e32 v52, v170
	v_mov_b32_e32 v53, v171
	v_mov_b32_e32 v54, v172
	v_mov_b32_e32 v55, v173
	v_mov_b32_e32 v48, v174
	v_mov_b32_e32 v49, v175
	v_mov_b32_e32 v50, v176
	v_mov_b32_e32 v51, v177
	v_mov_b32_e32 v76, v178
	v_mov_b32_e32 v77, v179
	v_mov_b32_e32 v78, v180
	v_mov_b32_e32 v79, v181
	v_mov_b32_e32 v72, v182
	v_mov_b32_e32 v73, v183
	v_mov_b32_e32 v74, v184
	v_mov_b32_e32 v75, v185
	v_mov_b32_e32 v68, v186
	v_mov_b32_e32 v69, v187
	v_mov_b32_e32 v70, v188
	v_mov_b32_e32 v71, v189
	v_mov_b32_e32 v64, v190
	v_mov_b32_e32 v65, v191
	v_mov_b32_e32 v66, v192
	v_mov_b32_e32 v67, v193
	v_mov_b32_e32 v118, v194
	v_pk_mul_f32 v[102:103], v[102:103], v[118:119] op_sel_hi:[1,0]
	s_waitcnt lgkmcnt(7)
	v_mfma_f32_16x16x32_bf16 v[138:141], v[52:55], v[130:133], 0
	v_mul_f32_e64 v100, v100, v118
	v_mul_f32_e64 v101, v101, v118
	s_add_i32 s13, s12, 2
	s_waitcnt lgkmcnt(3)
	v_mfma_f32_16x16x32_bf16 v[138:141], v[48:51], v[150:153], v[138:141]
	v_mfma_f32_16x16x32_bf16 v[154:157], v[52:55], v[134:137], 0
	s_nop 6
	v_sub_f32_e32 v79, v79, v141
	v_sub_f32_e32 v78, v78, v140
	v_sub_f32_e32 v77, v77, v139
	v_sub_f32_e32 v76, v76, v138
	v_cvt_pk_bf16_f32 v138, v76, v77
	v_cvt_pk_bf16_f32 v139, v78, v79
	s_waitcnt lgkmcnt(2)
	v_mfma_f32_16x16x32_bf16 v[76:79], v[48:51], v[158:161], v[154:157]
	s_nop 7
	v_sub_f32_e32 v79, v75, v79
	v_sub_f32_e32 v78, v74, v78
	v_sub_f32_e32 v77, v73, v77
	v_sub_f32_e32 v76, v72, v76
	v_mfma_f32_16x16x32_bf16 v[72:75], v[52:55], v[142:145], 0
	v_cvt_pk_bf16_f32 v76, v76, v77
	v_cvt_pk_bf16_f32 v77, v78, v79
	ds_write2st64_b64 v127, v[138:139], v[76:77] offset0:32 offset1:34
	v_mfma_f32_16x16x32_bf16 v[52:55], v[52:55], v[146:149], 0
	v_mul_f32_e64 v78, v110, v118
	v_mul_f32_e64 v79, v111, v118
	v_pk_mul_f32 v[76:77], v[108:109], v[118:119] op_sel_hi:[1,0]
	s_waitcnt lgkmcnt(2)
	v_mfma_f32_16x16x32_bf16 v[72:75], v[48:51], v[162:165], v[72:75]
	s_waitcnt lgkmcnt(1)
	v_mfma_f32_16x16x32_bf16 v[48:51], v[48:51], v[166:169], v[52:55]
	s_nop 5
	v_sub_f32_e32 v71, v71, v75
	v_sub_f32_e32 v70, v70, v74
	v_sub_f32_e32 v69, v69, v73
	v_sub_f32_e32 v68, v68, v72
	v_sub_f32_e32 v51, v67, v51
	v_sub_f32_e32 v50, v66, v50
	v_sub_f32_e32 v49, v65, v49
	v_sub_f32_e32 v48, v64, v48
	v_cvt_pk_bf16_f32 v68, v68, v69
	v_cvt_pk_bf16_f32 v69, v70, v71
	v_cvt_pk_bf16_f32 v48, v48, v49
	v_cvt_pk_bf16_f32 v49, v50, v51
	ds_write_b64 v128, v[68:69] offset:16384
	ds_write_b64 v129, v[48:49] offset:16384
	s_waitcnt vmcnt(13)
	v_mfma_f32_16x16x32_bf16 v[48:51], v[4:7], v[130:133], 0
	s_waitcnt lgkmcnt(0)
	s_barrier
	s_min_u32 s24, s13, 0x7d
	s_add_i32 s24, s24, s8
	s_ashr_i32 s25, s24, 31
	s_lshl_b64 s[26:27], s[24:25], 12
	v_lshl_add_u64 v[222:223], s[26:27], 0, v[112:113]
	v_lshlrev_b64 v[222:223], 1, v[222:223]
	v_lshl_add_u64 v[222:223], s[20:21], 0, v[222:223]
	s_lshl_b64 s[26:27], s[24:25], 14
	v_lshl_add_u64 v[224:225], v[116:117], 0, s[26:27]
	s_lshl_b64 s[28:29], s[24:25], 2
	s_add_u32 s28, s10, s28
	s_addc_u32 s29, s11, s29
	global_load_dwordx4 v[170:173], v[222:223], off
	global_load_dwordx4 v[174:177], v[222:223], off offset:1024
	global_load_dwordx4 v[178:181], v[224:225], off
	global_load_dwordx4 v[182:185], v[224:225], off offset:1024
	global_load_dwordx4 v[186:189], v[224:225], off offset:2048
	global_load_dwordx4 v[190:193], v[224:225], off offset:3072
	global_load_dword v194, v125, s[28:29]
	v_mfma_f32_16x16x32_bf16 v[48:51], v[16:19], v[150:153], v[48:51]
	ds_read_b128 v[52:55], v126 offset:16384
	ds_read_b128 v[64:67], v126 offset:17408
	ds_read_b128 v[68:71], v126 offset:20480
	ds_read_b128 v[72:75], v126 offset:21504
	s_waitcnt lgkmcnt(3)
	v_mfma_f32_16x16x32_bf16 v[48:51], v[0:3], v[52:55], v[48:51]
	v_mfma_f32_16x16x32_bf16 v[52:55], v[8:11], v[52:55], v[76:79]
	s_waitcnt lgkmcnt(1)
	v_mfma_f32_16x16x32_bf16 v[108:111], v[12:15], v[68:71], v[52:55]
	v_mfma_f32_16x16x32_bf16 v[52:55], v[4:7], v[134:137], 0
	v_mfma_f32_16x16x32_bf16 v[52:55], v[16:19], v[158:161], v[52:55]
	v_mfma_f32_16x16x32_bf16 v[48:51], v[20:23], v[68:71], v[48:51]
	v_mul_f32_e64 v70, v106, v118
	v_mul_f32_e64 v71, v107, v118
	v_pk_mul_f32 v[68:69], v[104:105], v[118:119] op_sel_hi:[1,0]
	v_mfma_f32_16x16x32_bf16 v[52:55], v[0:3], v[64:67], v[52:55]
	s_nop 0
	v_mfma_f32_16x16x32_bf16 v[64:67], v[8:11], v[64:67], v[68:71]
	s_waitcnt lgkmcnt(0)
	v_mfma_f32_16x16x32_bf16 v[104:107], v[12:15], v[72:75], v[64:67]
	v_mfma_f32_16x16x32_bf16 v[64:67], v[4:7], v[142:145], 0
	v_mfma_f32_16x16x32_bf16 v[4:7], v[4:7], v[146:149], 0
	v_mfma_f32_16x16x32_bf16 v[52:55], v[20:23], v[72:75], v[52:55]
	ds_read_b128 v[68:71], v126 offset:18432
	ds_read_b128 v[72:75], v126 offset:19456
	ds_read_b128 v[76:79], v126 offset:22528
	ds_read_b128 v[130:133], v126 offset:23552
	v_mfma_f32_16x16x32_bf16 v[64:67], v[16:19], v[162:165], v[64:67]
	v_mfma_f32_16x16x32_bf16 v[4:7], v[16:19], v[166:169], v[4:7]
	v_cvt_pk_bf16_f32 v16, v104, v105
	v_cvt_pk_bf16_f32 v17, v106, v107
	s_waitcnt lgkmcnt(3)
	v_mfma_f32_16x16x32_bf16 v[64:67], v[0:3], v[68:71], v[64:67]
	s_waitcnt lgkmcnt(2)
	v_mfma_f32_16x16x32_bf16 v[0:3], v[0:3], v[72:75], v[4:7]
	s_nop 2
	v_mul_f32_e64 v6, v98, v118
	v_mul_f32_e64 v7, v99, v118
	v_pk_mul_f32 v[4:5], v[96:97], v[118:119] op_sel_hi:[1,0]
	v_mfma_f32_16x16x32_bf16 v[68:71], v[8:11], v[68:71], v[100:103]
	s_nop 0
	v_mfma_f32_16x16x32_bf16 v[4:7], v[8:11], v[72:75], v[4:7]
	s_waitcnt lgkmcnt(1)
; __device__ __forceinline__ uint2 pack4v(f32x4 a) { uint2 r; r.x = pack2(a[0], a[1]); r.y = pack2(a[2], a[3]); return r; }
; __device__ __forceinline__ f32x4 mfma16(bf16x8 a, bf16x8 b, f32x4 c) { return __builtin_amdgcn_mfma_f32_16x16x32_bf16(a, b, c, 0, 0, 0); }
; __device__ __forceinline__ void scan_load(const ScanCtx& c, int n, bf16x8 (&W_)[2], bf16x8 (&QH_)[2], bf16x8 (&QK_)[2],
;                                           bf16x8 (&KT_)[2], f32x4 (&U_)[4], float& g_) {
;   n = n < 128 ? n : 127;
;   const size_t cb = (size_t)(c.seq * 128 + n) * 4096;
; #pragma unroll
;   for (int kb = 0; kb < 2; ++kb) {
;     const size_t o = cb + ((c.w * 2 + kb) * 64 + c.lane) * 8;
;     W_[kb] = *(const bf16x8*)(c.DNW + o); QH_[kb] = *(const bf16x8*)(c.DNQH + o); QK_[kb] = *(const bf16x8*)(c.DNQK + o); KT_[kb] = *(const bf16x8*)(c.DNKT + o);
;   }
; #pragma unroll
;   for (int nt = 0; nt < 4; ++nt) U_[nt] = *(const f32x4*)(c.Ubuf + cb + ((c.w * 4 + nt) * 64 + c.lane) * 4);
;   g_ = c.glp[c.seq * 128 + n];
; }
; __device__ __forceinline__ void scan_step(const ScanCtx& c, int n, const u16* Sc, u16* Sn, f32x4 (&S)[4], bf16x8 (&W_)[2], ...
;     ...
; #pragma unroll
;   for (int nt = 0; nt < 4; ++nt) {
;     f32x4 o = {0.f, 0.f, 0.f, 0.f};
;     o = mfma16(QH_[0], Sf[0][nt], o); o = mfma16(QH_[1], Sf[1][nt], o);
;     o = mfma16(QK_[0], Vf[0][nt], o); o = mfma16(QK_[1], Vf[1][nt], o);
;     *(f32x4*)(c.Obuf + cb + ((w * 4 + nt) * 64 + lane) * 4) = o;
;     f32x4 sv = S[nt] * glc;
;     sv = mfma16(KT_[0], Vf[0][nt], sv); sv = mfma16(KT_[1], Vf[1][nt], sv);
;     S[nt] = sv;
;     *(uint2*)(Sn + (((w >> 1) * 4 + nt) * 64 + lane) * 8 + (w & 1) * 4) = pack4v(sv);
;   }
;   __builtin_amdgcn_sched_barrier(0);
;   scan_load(c, n + 2, W_, QH_, QK_, KT_, U_, g_);
	v_mfma_f32_16x16x32_bf16 v[100:103], v[12:15], v[76:79], v[68:71]
	s_waitcnt lgkmcnt(0)
	v_mfma_f32_16x16x32_bf16 v[0:3], v[20:23], v[130:133], v[0:3]
	s_nop 1
	v_add_co_u32_e32 v68, vcc, s9, v120
	v_mfma_f32_16x16x32_bf16 v[96:99], v[12:15], v[130:133], v[4:7]
	s_nop 0
	v_addc_co_u32_e32 v69, vcc, -1, v121, vcc
	global_store_dwordx4 v[68:69], v[48:51], off offset:-3072
	v_mfma_f32_16x16x32_bf16 v[64:67], v[20:23], v[76:79], v[64:67]
	global_store_dwordx4 v[68:69], v[0:3], off
	v_cvt_pk_bf16_f32 v48, v108, v109
	v_cvt_pk_bf16_f32 v49, v110, v111
	ds_write2st64_b64 v127, v[48:49], v[16:17] offset0:16 offset1:18
	v_cvt_pk_bf16_f32 v16, v100, v101
	v_cvt_pk_bf16_f32 v17, v102, v103
	v_cvt_pk_bf16_f32 v0, v96, v97
	v_cvt_pk_bf16_f32 v1, v98, v99
	global_store_dwordx4 v[68:69], v[52:55], off offset:-2048
	global_store_dwordx4 v[68:69], v[64:67], off offset:-1024
	ds_write_b64 v128, v[16:17] offset:8192
	ds_write_b64 v129, v[0:1] offset:8192
	s_min_u32 s14, s13, 0x7d
	s_add_i32 s14, s14, s8
	s_ashr_i32 s15, s14, 31
	s_lshl_b64 s[16:17], s[14:15], 12
	v_lshl_add_u64 v[0:1], s[16:17], 0, v[112:113]
	v_lshlrev_b64 v[8:9], 1, v[0:1]
	v_lshl_add_u64 v[12:13], s[0:1], 0, v[8:9]
	v_lshl_add_u64 v[10:11], s[20:21], 0, v[8:9]
	v_lshl_add_u64 v[14:15], s[2:3], 0, v[8:9]
	global_load_dwordx4 v[4:7], v[12:13], off
	global_load_dwordx4 v[0:3], v[14:15], off
	v_lshl_add_u64 v[12:13], s[4:5], 0, v[8:9]
	v_lshl_add_u64 v[8:9], s[16:17], 0, v[114:115]
	v_lshlrev_b64 v[14:15], 1, v[8:9]
	v_lshl_add_u64 v[20:21], s[0:1], 0, v[14:15]
	v_lshl_add_u64 v[64:65], s[2:3], 0, v[14:15]
	s_lshl_b64 s[16:17], s[14:15], 14
	s_nop 0
	s_nop 0
	s_nop 0
	global_load_dwordx4 v[8:11], v[12:13], off
	global_load_dwordx4 v[16:19], v[20:21], off
	v_lshl_add_u64 v[66:67], s[4:5], 0, v[14:15]
	global_load_dwordx4 v[20:23], v[64:65], off
	global_load_dwordx4 v[12:15], v[66:67], off
	v_lshl_add_u64 v[64:65], v[116:117], 0, s[16:17]
	s_lshl_b64 s[14:15], s[14:15], 2
	s_nop 0
	s_nop 0
	s_nop 0
	s_nop 0
	s_nop 0
	s_add_u32 s14, s10, s14
	s_addc_u32 s15, s11, s15
	s_nop 0
	s_waitcnt lgkmcnt(0)
	s_barrier
	ds_read_b128 v[130:133], v126 offset:8192
	ds_read_b128 v[134:137], v126 offset:9216
	ds_read_b128 v[138:141], v126 offset:10240
	ds_read_b128 v[142:145], v126 offset:11264
	ds_read_b128 v[146:149], v126 offset:12288
	s_waitcnt vmcnt(19) lgkmcnt(4)
	v_mov_b32_e32 v60, v196
	v_mov_b32_e32 v61, v197
	v_mov_b32_e32 v62, v198
	v_mov_b32_e32 v63, v199
	v_mov_b32_e32 v56, v200
	v_mov_b32_e32 v57, v201
	v_mov_b32_e32 v58, v202
	v_mov_b32_e32 v59, v203
	v_mov_b32_e32 v92, v204
	v_mov_b32_e32 v93, v205
	v_mov_b32_e32 v94, v206
	v_mov_b32_e32 v95, v207
	v_mov_b32_e32 v88, v208
	v_mov_b32_e32 v89, v209
	v_mov_b32_e32 v90, v210
	v_mov_b32_e32 v91, v211
	v_mov_b32_e32 v84, v212
	v_mov_b32_e32 v85, v213
	v_mov_b32_e32 v86, v214
	v_mov_b32_e32 v87, v215
	v_mov_b32_e32 v80, v216
	v_mov_b32_e32 v81, v217
	v_mov_b32_e32 v82, v218
	v_mov_b32_e32 v83, v219
	v_mov_b32_e32 v122, v195
	v_mfma_f32_16x16x32_bf16 v[150:153], v[60:63], v[130:133], 0
	ds_read_b128 v[154:157], v126 offset:13312
	ds_read_b128 v[158:161], v126 offset:14336
	ds_read_b128 v[162:165], v126 offset:15360
	s_nop 0
	v_pk_mul_f32 v[102:103], v[122:123], v[102:103] op_sel_hi:[0,1]
	v_pk_mul_f32 v[100:101], v[122:123], v[100:101] op_sel_hi:[0,1]
	s_waitcnt lgkmcnt(3)
	v_mfma_f32_16x16x32_bf16 v[150:153], v[56:59], v[146:149], v[150:153]
	s_add_i32 s12, s12, 3
	v_mfma_f32_16x16x32_bf16 v[166:169], v[60:63], v[134:137], 0
	s_nop 0
	s_nop 4
	v_sub_f32_e32 v95, v95, v153
	v_sub_f32_e32 v94, v94, v152
	v_sub_f32_e32 v93, v93, v151
	v_sub_f32_e32 v92, v92, v150
	v_cvt_pk_bf16_f32 v150, v92, v93
	v_cvt_pk_bf16_f32 v151, v94, v95
	s_waitcnt lgkmcnt(2)
	v_mfma_f32_16x16x32_bf16 v[92:95], v[56:59], v[154:157], v[166:169]
	s_nop 0
	s_nop 6
	v_sub_f32_e32 v95, v91, v95
	v_sub_f32_e32 v94, v90, v94
	v_sub_f32_e32 v93, v89, v93
	v_sub_f32_e32 v92, v88, v92
	v_mfma_f32_16x16x32_bf16 v[88:91], v[60:63], v[138:141], 0
	v_cvt_pk_bf16_f32 v92, v92, v93
	v_cvt_pk_bf16_f32 v93, v94, v95
	ds_write2st64_b64 v127, v[150:151], v[92:93] offset0:32 offset1:34
	v_mfma_f32_16x16x32_bf16 v[60:63], v[60:63], v[142:145], 0
	v_mul_f32_e64 v94, v122, v110
	v_mul_f32_e64 v95, v122, v111
	v_pk_mul_f32 v[92:93], v[122:123], v[108:109] op_sel_hi:[0,1]
	s_waitcnt lgkmcnt(2)
	v_mfma_f32_16x16x32_bf16 v[88:91], v[56:59], v[158:161], v[88:91]
	s_waitcnt lgkmcnt(1)
	v_mfma_f32_16x16x32_bf16 v[56:59], v[56:59], v[162:165], v[60:63]
	s_nop 0
	s_nop 4
	v_sub_f32_e32 v87, v87, v91
	v_sub_f32_e32 v86, v86, v90
	v_sub_f32_e32 v85, v85, v89
	v_sub_f32_e32 v84, v84, v88
	s_nop 0
	v_sub_f32_e32 v59, v83, v59
	v_sub_f32_e32 v58, v82, v58
	v_sub_f32_e32 v57, v81, v57
	v_sub_f32_e32 v56, v80, v56
	v_cvt_pk_bf16_f32 v84, v84, v85
	v_cvt_pk_bf16_f32 v85, v86, v87
	v_cvt_pk_bf16_f32 v56, v56, v57
	v_cvt_pk_bf16_f32 v57, v58, v59
	ds_write_b64 v128, v[84:85] offset:16384
	ds_write_b64 v129, v[56:57] offset:16384
	s_waitcnt vmcnt(13)
	v_mfma_f32_16x16x32_bf16 v[56:59], v[28:31], v[130:133], 0
	s_waitcnt lgkmcnt(0)
	s_barrier
; __device__ __forceinline__ uint2 pack4v(f32x4 a) { uint2 r; r.x = pack2(a[0], a[1]); r.y = pack2(a[2], a[3]); return r; }
; __device__ __forceinline__ f32x4 mfma16(bf16x8 a, bf16x8 b, f32x4 c) { return __builtin_amdgcn_mfma_f32_16x16x32_bf16(a, b, c, 0, 0, 0); }
; __device__ __forceinline__ void scan_step(const ScanCtx& c, int n, const u16* Sc, u16* Sn, f32x4 (&S)[4], bf16x8 (&W_)[2], ...
;     ...
; #pragma unroll
;   for (int nt = 0; nt < 4; ++nt) {
;     f32x4 o = {0.f, 0.f, 0.f, 0.f};
;     o = mfma16(QH_[0], Sf[0][nt], o); o = mfma16(QH_[1], Sf[1][nt], o);
;     o = mfma16(QK_[0], Vf[0][nt], o); o = mfma16(QK_[1], Vf[1][nt], o);
;     *(f32x4*)(c.Obuf + cb + ((w * 4 + nt) * 64 + lane) * 4) = o;
;     f32x4 sv = S[nt] * glc;
;     sv = mfma16(KT_[0], Vf[0][nt], sv); sv = mfma16(KT_[1], Vf[1][nt], sv);
;     S[nt] = sv;
;     *(uint2*)(Sn + (((w >> 1) * 4 + nt) * 64 + lane) * 8 + (w & 1) * 4) = pack4v(sv);
;   }
;   __builtin_amdgcn_sched_barrier(0);
;   scan_load(c, n + 2, W_, QH_, QK_, KT_, U_, g_);
;   {
;     tr[0] ^= tr[1] ^ tr[4];
;     tr[1] = tr[2]; tr[4] = tr[5]; tr[2] = tr[3]; tr[5] = tr[6];
;     const size_t pb = (size_t)(c.seq * 128 + (n + 5 < 128 ? n + 5 : 127)) * 4096;
;     const u16* arr4 = (lane >> 4) == 0 ? c.DNW : ((lane >> 4) == 1 ? c.DNQH : ((lane >> 4) == 2 ? c.DNQK : c.DNKT));
;     tr[3] = *(const unsigned*)(arr4 + pb + w * 1024 + (lane & 15) * 64);
;     tr[6] = *(const unsigned*)(c.Ubuf + pb + w * 1024 + (lane & 31) * 32);
;   }
;   __syncthreads();
; }
; __device__ void scan_seq(const P& p, int seq, u16* lds) {
;     ...
;   if ((tr[0] ^ tr[1] ^ tr[2] ^ tr[3] ^ tr[4] ^ tr[5] ^ tr[6]) == 0x9e3779b9u && seq == 4097) p_gl[0] = 0.f;
; #pragma unroll
;   for (int nt = 0; nt < 4; ++nt)
; #pragma unroll
;     for (int r = 0; r < 4; ++r) p.out[O_DP + ((size_t)seq * 64 + w * 16 + fq * 4 + r) * 64 + nt * 16 + fr] = S[nt][r];
	s_min_u32 s24, s12, 0x7d
	s_add_i32 s24, s24, s8
	s_ashr_i32 s25, s24, 31
	s_lshl_b64 s[26:27], s[24:25], 12
	v_lshl_add_u64 v[222:223], s[26:27], 0, v[112:113]
	v_lshlrev_b64 v[222:223], 1, v[222:223]
	v_lshl_add_u64 v[222:223], s[20:21], 0, v[222:223]
	s_lshl_b64 s[26:27], s[24:25], 14
	v_lshl_add_u64 v[224:225], v[116:117], 0, s[26:27]
	s_lshl_b64 s[28:29], s[24:25], 2
	s_add_u32 s28, s10, s28
	s_addc_u32 s29, s11, s29
	global_load_dwordx4 v[196:199], v[222:223], off
	global_load_dwordx4 v[200:203], v[222:223], off offset:1024
	global_load_dwordx4 v[204:207], v[224:225], off
	global_load_dwordx4 v[208:211], v[224:225], off offset:1024
	global_load_dwordx4 v[212:215], v[224:225], off offset:2048
	global_load_dwordx4 v[216:219], v[224:225], off offset:3072
	global_load_dword v195, v125, s[28:29]
	v_mfma_f32_16x16x32_bf16 v[56:59], v[40:43], v[146:149], v[56:59]
	ds_read_b128 v[60:63], v126 offset:16384
	ds_read_b128 v[80:83], v126 offset:17408
	ds_read_b128 v[84:87], v126 offset:20480
	ds_read_b128 v[88:91], v126 offset:21504
	s_waitcnt lgkmcnt(3)
	v_mfma_f32_16x16x32_bf16 v[56:59], v[24:27], v[60:63], v[56:59]
	v_mfma_f32_16x16x32_bf16 v[60:63], v[32:35], v[60:63], v[92:95]
	s_waitcnt lgkmcnt(1)
	v_mfma_f32_16x16x32_bf16 v[108:111], v[36:39], v[84:87], v[60:63]
	v_mfma_f32_16x16x32_bf16 v[60:63], v[28:31], v[134:137], 0
	v_mfma_f32_16x16x32_bf16 v[60:63], v[40:43], v[154:157], v[60:63]
	v_mfma_f32_16x16x32_bf16 v[56:59], v[44:47], v[84:87], v[56:59]
	v_mul_f32_e64 v86, v122, v106
	v_mul_f32_e64 v87, v122, v107
	v_pk_mul_f32 v[84:85], v[122:123], v[104:105] op_sel_hi:[0,1]
	v_mfma_f32_16x16x32_bf16 v[60:63], v[24:27], v[80:83], v[60:63]
	s_nop 0
	v_mfma_f32_16x16x32_bf16 v[80:83], v[32:35], v[80:83], v[84:87]
	s_waitcnt lgkmcnt(0)
	v_mfma_f32_16x16x32_bf16 v[104:107], v[36:39], v[88:91], v[80:83]
	v_mfma_f32_16x16x32_bf16 v[80:83], v[28:31], v[138:141], 0
	v_mfma_f32_16x16x32_bf16 v[28:31], v[28:31], v[142:145], 0
	v_mfma_f32_16x16x32_bf16 v[60:63], v[44:47], v[88:91], v[60:63]
	ds_read_b128 v[84:87], v126 offset:18432
	ds_read_b128 v[88:91], v126 offset:19456
	ds_read_b128 v[92:95], v126 offset:22528
	ds_read_b128 v[130:133], v126 offset:23552
	global_store_dwordx4 v[120:121], v[56:59], off offset:-3072
	v_mfma_f32_16x16x32_bf16 v[80:83], v[40:43], v[158:161], v[80:83]
	s_nop 1
	global_store_dwordx4 v[120:121], v[60:63], off offset:-2048
	v_cvt_pk_bf16_f32 v56, v108, v109
	v_cvt_pk_bf16_f32 v57, v110, v111
	v_mfma_f32_16x16x32_bf16 v[28:31], v[40:43], v[162:165], v[28:31]
	v_cvt_pk_bf16_f32 v40, v104, v105
	v_cvt_pk_bf16_f32 v41, v106, v107
	ds_write2st64_b64 v127, v[56:57], v[40:41] offset1:2
	s_waitcnt lgkmcnt(4)
	v_mfma_f32_16x16x32_bf16 v[80:83], v[24:27], v[84:87], v[80:83]
	s_waitcnt lgkmcnt(3)
	v_mfma_f32_16x16x32_bf16 v[24:27], v[24:27], v[88:91], v[28:31]
	s_nop 2
	v_mul_f32_e64 v30, v122, v98
	v_mul_f32_e64 v31, v122, v99
	v_pk_mul_f32 v[28:29], v[122:123], v[96:97] op_sel_hi:[0,1]
	v_mfma_f32_16x16x32_bf16 v[84:87], v[32:35], v[84:87], v[100:103]
	s_nop 0
	v_mfma_f32_16x16x32_bf16 v[28:31], v[32:35], v[88:91], v[28:31]
	s_waitcnt lgkmcnt(2)
	v_mfma_f32_16x16x32_bf16 v[100:103], v[36:39], v[92:95], v[84:87]
	s_waitcnt lgkmcnt(1)
	v_mfma_f32_16x16x32_bf16 v[24:27], v[44:47], v[130:133], v[24:27]
	v_mfma_f32_16x16x32_bf16 v[96:99], v[36:39], v[130:133], v[28:31]
	s_nop 4
	v_cvt_pk_bf16_f32 v40, v100, v101
	v_cvt_pk_bf16_f32 v41, v102, v103
	global_store_dwordx4 v[120:121], v[24:27], off
	v_mfma_f32_16x16x32_bf16 v[80:83], v[44:47], v[92:95], v[80:83]
	ds_write_b64 v128, v[40:41]
	v_cvt_pk_bf16_f32 v24, v96, v97
	v_cvt_pk_bf16_f32 v25, v98, v99
	ds_write_b64 v129, v[24:25]
	s_nop 3
	global_store_dwordx4 v[120:121], v[80:83], off offset:-1024
	s_min_u32 s12, s12, 0x7d
	s_add_i32 s14, s12, s8
	s_ashr_i32 s15, s14, 31
	s_lshl_b64 s[16:17], s[14:15], 12
	v_lshl_add_u64 v[24:25], s[16:17], 0, v[112:113]
	v_lshlrev_b64 v[32:33], 1, v[24:25]
	v_lshl_add_u64 v[34:35], s[20:21], 0, v[32:33]
	v_lshl_add_u64 v[24:25], s[0:1], 0, v[32:33]
	v_lshl_add_u64 v[26:27], s[2:3], 0, v[32:33]
	v_lshl_add_u64 v[36:37], s[4:5], 0, v[32:33]
	v_lshl_add_u64 v[32:33], s[16:17], 0, v[114:115]
	v_lshlrev_b64 v[38:39], 1, v[32:33]
	v_lshl_add_u64 v[44:45], s[0:1], 0, v[38:39]
	v_lshl_add_u64 v[80:81], s[2:3], 0, v[38:39]
	s_lshl_b64 s[16:17], s[14:15], 14
	global_load_dwordx4 v[28:31], v[24:25], off
	s_nop 0
	global_load_dwordx4 v[24:27], v[26:27], off
	s_nop 0
	s_nop 0
	s_nop 0
	s_nop 0
	global_load_dwordx4 v[32:35], v[36:37], off
	global_load_dwordx4 v[40:43], v[44:45], off
	v_lshl_add_u64 v[82:83], s[4:5], 0, v[38:39]
	global_load_dwordx4 v[44:47], v[80:81], off
	global_load_dwordx4 v[36:39], v[82:83], off
	v_lshl_add_u64 v[80:81], v[116:117], 0, s[16:17]
	s_lshl_b64 s[14:15], s[14:15], 2
	s_nop 0
	s_nop 0
	s_nop 0
	s_nop 0
	s_nop 0
	s_add_u32 s14, s10, s14
	s_addc_u32 s15, s11, s15
	s_nop 0
	v_lshl_add_u64 v[120:121], v[120:121], 0, s[6:7]
	s_cmpk_lt_u32 s13, 0x7e
	s_mov_b32 s12, s13
	s_waitcnt lgkmcnt(0)
	s_barrier
	s_cbranch_scc1 .LBB0_483
	v_readlane_b32 s0, v228, 0
	v_readlane_b32 s1, v228, 1
	s_mov_b32 s2, s0
	s_ashr_i32 s3, s0, 31
	v_writelane_b32 v228, s0, 0
	s_waitcnt vmcnt(0)
	v_lshlrev_b32_e32 v0, 4, v124
	v_ashrrev_i32_e32 v1, 31, v0
	v_writelane_b32 v228, s1, 1
	s_lshl_b64 s[0:1], s[2:3], 6
	v_lshl_add_u64 v[0:1], s[0:1], 0, v[0:1]
	v_lshrrev_b32_e32 v3, 2, v123
	v_and_or_b32 v0, v3, 12, v0
	v_and_b32_e32 v2, 15, v123
	v_lshlrev_b64 v[0:1], 8, v[0:1]
	v_lshl_add_u64 v[0:1], s[20:21], 0, v[0:1]
	v_lshlrev_b32_e32 v2, 2, v2
	v_mov_b32_e32 v3, 0
	v_lshl_add_u64 v[0:1], v[0:1], 0, v[2:3]
	s_mov_b32 s0, 0x8492000
	v_add_co_u32_e32 v0, vcc, s0, v0
	s_nop 1
	v_addc_co_u32_e32 v1, vcc, 0, v1, vcc
	global_store_dword v[0:1], v108, off
	global_store_dword v[0:1], v109, off offset:256
	global_store_dword v[0:1], v110, off offset:512
	global_store_dword v[0:1], v111, off offset:768
	global_store_dword v[0:1], v104, off offset:64
	global_store_dword v[0:1], v105, off offset:320
	global_store_dword v[0:1], v106, off offset:576
	global_store_dword v[0:1], v107, off offset:832
	global_store_dword v[0:1], v100, off offset:128
	global_store_dword v[0:1], v101, off offset:384
	global_store_dword v[0:1], v102, off offset:640
	global_store_dword v[0:1], v103, off offset:896
	global_store_dword v[0:1], v96, off offset:192
	global_store_dword v[0:1], v97, off offset:448
	global_store_dword v[0:1], v98, off offset:704
	global_store_dword v[0:1], v99, off offset:960
; __device__ __forceinline__ int tid_() { int t = threadIdx.x; asm volatile("" : "+v"(t)); return t; }
; __device__ __forceinline__ unsigned xb_ld(unsigned* p)              { return __hip_atomic_load(p, __ATOMIC_RELAXED, __HIP_MEMORY_SCOPE_AGENT); }
; #define PHASE(i, call) if (p.ph_lo <= (i) && (i) < p.ph_hi) { if (PHON(i)) { call; } if ((i) + 1 < p.ph_hi) { XcdBarrier xb_; xb_.bar = p_bar; xb_.x = xb_xcc_id(); xb_.st = (volatile LAS unsigned*)&xb_words; xcd_barrier(xb_); } }
; __device__ __forceinline__ void xcd_barrier_complete(unsigned* bar, unsigned x, unsigned& nloc, unsigned& nx) {
;     const unsigned G = gridDim.x * gridDim.y * gridDim.z;
;     unsigned sum, cnt, mine, sp = 0u;
;     for (;;) {
;         sum = 0u; cnt = 0u; mine = 0u;
; #pragma unroll
;         for (unsigned j = 0; j < 16; ++j) { const unsigned c = xb_ld(&bar[XB_XCNT(j)]); sum += c; cnt += (c > 0u) ? 1u : 0u; mine = (j == x) ? c : mine; }
;         if (sum == G) break;
;         __builtin_amdgcn_s_sleep(1);
;         if ((++sp & 255u) == 0u) { if (xb_ld(&bar[XB_TMO])) break; if (sp > XB_SPIN_CAP) { atomicAdd(&bar[XB_TMO], 1u); break; } }
;     }
;     nloc = mine > 0u ? mine : 1u; nx = cnt > 0u ? cnt : 1u;
; }
; __device__ __forceinline__ void xcd_barrier(const XcdBarrier& b) {
;     asm volatile("s_waitcnt vmcnt(0)" ::: "memory");
;     __syncthreads();
;     if (tid_() == 0) {
;         unsigned* bar = b.bar;
;         __builtin_amdgcn_s_waitcnt(0);
;         unsigned nloc = b.st[0], nx = b.st[1];
;         if (nloc == 0u) { xcd_barrier_complete(bar, b.x, nloc, nx); b.st[0] = nloc; b.st[1] = nx; }
; __global__ void __launch_bounds__(256, 2) mega(P p) {
;     ...
;   if (p.ph_lo <= 0 && 0 < p.ph_hi) { if (PHON(0)) { ph_prep(p, lds_f); } if (1 < p.ph_hi) grid.sync(); }
;   PHASE(1, ph_gemm1(p, (u16*)lds_f))
;   PHASE(2, ph_dnpre(p, lds_f))
;   PHASE(3, ph_mixer(p, (u16*)lds_f))
;   PHASE(4, ph_gatenorm(p))
.LBB0_485:
	v_readlane_b32 s0, v227, 60
	v_readlane_b32 s1, v227, 61
	s_nop 1
	v_writelane_b32 v228, s0, 0
	v_writelane_b32 v228, s1, 10
	s_nop 1
	v_readlane_b32 s6, v228, 12
	v_readlane_b32 s7, v228, 13
	s_cmp_lt_i32 s7, 5
	s_cbranch_scc1 .LBB0_539
	s_getreg_b32 s2, hwreg(HW_REG_XCC_ID, 0, 4)
	s_waitcnt vmcnt(0)
	v_mov_b32_e32 v0, v220
	s_waitcnt vmcnt(0) lgkmcnt(0)
	s_barrier
	s_nop 0
	v_cmp_eq_u32_e32 vcc, 0, v0
	s_and_saveexec_b64 s[0:1], vcc
	s_cbranch_execz .LBB0_538
	v_mov_b32_e32 v0, 0
	s_waitcnt vmcnt(0) expcnt(0) lgkmcnt(0)
	ds_read_b32 v2, v0 offset:57344
	ds_read_b32 v1, v0 offset:57348
	s_and_b32 s33, s2, 15
	s_waitcnt lgkmcnt(1)
	v_cmp_ne_u32_e32 vcc, 0, v2
	s_cbranch_vccnz .LBB0_502
	v_readlane_b32 s2, v228, 10
	v_readlane_b32 s3, v228, 11
	v_readlane_b32 s4, v228, 14
	v_readlane_b32 s36, v228, 2
	s_mul_i32 s44, s3, s4
	v_readlane_b32 s42, v228, 8
	s_mul_i32 s44, s44, s2
	v_readlane_b32 s43, v228, 9
	s_add_u32 s2, s42, 0x179ed200
	s_addc_u32 s3, s43, 0
	s_add_u32 s4, s42, 0x179ed400
	s_addc_u32 s5, s43, 0
	s_add_u32 s6, s42, 0x179ed500
	s_addc_u32 s7, s43, 0
	s_add_u32 s8, s42, 0x179ed600
	s_addc_u32 s9, s43, 0
	s_add_u32 s10, s42, 0x179ed700
	s_addc_u32 s11, s43, 0
	s_add_u32 s12, s42, 0x179ed800
	s_addc_u32 s13, s43, 0
	s_add_u32 s14, s42, 0x179ed900
	s_addc_u32 s15, s43, 0
	s_add_u32 s16, s42, 0x179eda00
	s_addc_u32 s17, s43, 0
	s_add_u32 s18, s42, 0x179edb00
	s_addc_u32 s19, s43, 0
	s_add_u32 s20, s42, 0x179edc00
	s_addc_u32 s21, s43, 0
	s_add_u32 s22, s42, 0x179edd00
	s_addc_u32 s23, s43, 0
	s_add_u32 s24, s42, 0x179ede00
	s_addc_u32 s25, s43, 0
	s_add_u32 s26, s42, 0x179edf00
	s_addc_u32 s27, s43, 0
	s_add_u32 s28, s42, 0x179ee000
	s_addc_u32 s29, s43, 0
	s_add_u32 s30, s42, 0x179ee100
	s_addc_u32 s31, s43, 0
	s_add_u32 s34, s42, 0x179ee200
	s_addc_u32 s35, s43, 0
	v_readlane_b32 s37, v228, 3
	s_add_u32 s36, s42, 0x179ee300
	s_addc_u32 s37, s43, 0
	s_mov_b32 s45, 1
	v_readlane_b32 s38, v228, 4
	v_readlane_b32 s39, v228, 5
	v_readlane_b32 s40, v228, 6
	v_readlane_b32 s41, v228, 7
	s_branch .LBB0_490
